# attention units: static s_setprio 1 for waves 4-7 (second wave of each SIMD) during full and quarter attention units, reset before grid barrier 2
# baseline (speedup 1.0000x reference)
; #define LAS __attribute__((address_space(3)))
; __device__ __forceinline__ void attn_unit(LAS unsigned char* lds, int unit, int mode, const bf16* QKVG, const float* sinks, const float* gain_a, bf16* MIX, float* SSA) {
;     const int tid = threadIdx.x, lane = tid & 63, w = __builtin_amdgcn_readfirstlane(tid >> 6);
;     const int kvh = unit & 1, blk = unit >> 1, nblk = blk & 15, T0 = blk * 128;
;     const int hl = (mode == 0 || mode >= 3) ? w : (4 * (mode - 1) + (w & 3));
;     const int i0 = (mode == 0) ? 0 : (mode <= 2) ? 2 * (w >> 2) : (mode - 3), i1 = (mode == 0) ? 4 : (mode <= 2) ? i0 + 2 : i0 + 1;
;     LAS bf16* Ks = (LAS bf16*)(lds + LDS_KS); LAS bf16* Vt = (LAS bf16*)(lds + LDS_VT); LAS float* SS = (LAS float*)(lds + LDS_SS);
;     const int h = kvh * 8 + hl, q = lane & 31, hh = lane >> 5;
;     SS[tid] = 0.f; SS[tid + 512] = 0.f;
;     const int r8 = lane >> 3, c8 = lane & 7;
;     const bf16* qrow0 = QKVG + (size_t)(T0 + r8) * QP + h * 64 + 8 * c8;
;     const bf16* grow0 = qrow0 + 1280;
;     LAS bf16* WT = (LAS bf16*)(lds + LDS_WT) + w * (32 * KP);
;     LAS bf16* wt_row = WT + r8 * KP + 8 * c8;
;     LAS bf16* wt_frq = WT + q * KP + 8 * hh;
;     LAS bf16* wt_frd = WT + q * KP + 4 * hh;
;     bf16x8 qr[4]; v2u gt[8]; v4u qrow[4], grow[4];
; #pragma unroll
;     for (int k = 0; k < 4; ++k) qrow[k] = __builtin_nontemporal_load((const v4u*)(qrow0 + (size_t)(32 * i0 + 8 * k) * QP));
;     if (mode < 3 || tid < 320) {
;         const int rp = ((mode >= 3) ? 16 * (mode - 3) : 0) + (tid >> 2), qd = tid & 3, row = 2 * rp;
;         const bool valid = (nblk > 0) || (row >= 128);
;         const int tok = valid ? (T0 - 128 + row) : T0;
;         const bf16* src = QKVG + (size_t)tok * QP + 1024 + kvh * 64 + qd * 16;
;         v4u k0[2], k1[2], v0[2], v1[2];
; #pragma unroll
;         for (int c = 0; c < 2; ++c) { k0[c] = *(const v4u*)(src + 8 * c); k1[c] = *(const v4u*)(src + QP + 8 * c); v0[c] = *(const v4u*)(src + 128 + 8 * c); v1[c] = *(const v4u*)(src + QP + 128 + 8 * c);
;             if (!valid) { k0[c] = k1[c] = v0[c] = v1[c] = (v4u){0u, 0u, 0u, 0u}; } }
.LBB0_290:
	v_writelane_b32 v253, s54, 50
	s_nop 1
	v_writelane_b32 v253, s55, 51
	s_or_b64 exec, exec, s[0:1]
	v_readlane_b32 s0, v253, 29
	s_nop 2
	s_cmp_lt_u32 s0, 4
	s_cbranch_scc1 .Lprio_skip_f
	s_setprio 1
.Lprio_skip_f:
	s_lshl_b32 s0, s33, 11
	s_lshl_b32 s1, s90, 6
	v_readfirstlane_b32 s12, v230
	s_bfe_u32 s91, s98, 0x10003
	s_add_i32 s0, s0, s1
	v_readlane_b32 s2, v253, 50
	s_lshr_b32 s10, s12, 6
	s_and_b32 s92, s0, 0xffffff80
	s_lshl_b32 s0, s91, 3
	v_lshrrev_b32_e32 v127, 3, v231
	v_readlane_b32 s3, v253, 51
	s_add_i32 s13, s10, s0
	v_or_b32_e32 v133, s92, v127
	s_movk_i32 s14, 0x1200
	v_mov_b64_e32 v[8:9], s[2:3]
	v_lshlrev_b32_e32 v2, 3, v230
	s_mov_b32 s1, 0
	v_mov_b32_e32 v131, 0
	v_mad_u64_u32 v[0:1], s[2:3], v133, s14, v[8:9]
	s_lshl_b32 s0, s13, 7
	v_and_b32_e32 v130, 56, v2
	v_lshl_add_u64 v[0:1], v[0:1], 0, s[0:1]
	v_lshlrev_b32_e32 v98, 1, v130
	v_mov_b32_e32 v99, v131
	v_lshl_add_u64 v[100:101], v[0:1], 0, v[98:99]
	s_mov_b32 s0, 0x9000
	v_add_co_u32_e32 v12, vcc, s0, v100
	s_mov_b32 s0, 0x12000
	s_nop 0
	v_addc_co_u32_e32 v13, vcc, 0, v101, vcc
	v_add_co_u32_e32 v0, vcc, s0, v100
	s_mov_b32 s0, 0x1b000
	s_nop 0
	v_addc_co_u32_e32 v1, vcc, 0, v101, vcc
	s_lshl_b32 s11, s13, 6
	v_add_co_u32_e32 v4, vcc, s0, v100
	s_and_b32 s93, s98, 0xf0
	s_nop 0
	v_addc_co_u32_e32 v5, vcc, 0, v101, vcc
	s_cmp_lg_u32 s93, 0
	s_movk_i32 s0, 0xff
	v_lshlrev_b32_e32 v52, 1, v103
	s_cselect_b64 vcc, -1, 0
	v_cmp_lt_u32_e64 s[4:5], s0, v230
	v_add_u32_e32 v10, 0xffffff80, v52
	s_or_b64 s[4:5], vcc, s[4:5]
	v_cndmask_b32_e64 v10, 0, v10, s[4:5]
	v_add_u32_e32 v10, s92, v10
	v_mad_i64_i32 v[8:9], s[2:3], v10, s14, v[8:9]
	s_lshl_b32 s0, s91, 7
	v_lshl_add_u64 v[8:9], v[8:9], 0, s[0:1]
	v_lshlrev_b32_e32 v50, 1, v102
	v_mov_b32_e32 v51, v131
	v_lshl_add_u64 v[32:33], v[8:9], 0, v[50:51]
	s_movk_i32 s0, 0x1000
	v_add_co_u32_e64 v20, s[6:7], s0, v32
	s_nop 1
	v_addc_co_u32_e64 v21, s[6:7], 0, v33, s[6:7]
	s_barrier
	global_load_dwordx4 v[0:3], v[0:1], off nt
	s_nop 0
	global_load_dwordx4 v[4:7], v[4:5], off nt
	s_nop 0
	global_load_dwordx4 v[8:11], v[100:101], off nt
	global_load_dwordx4 v[24:27], v[32:33], off offset:2048
	s_nop 0
	global_load_dwordx4 v[12:15], v[12:13], off nt
	s_nop 0
	global_load_dwordx4 v[16:19], v[32:33], off offset:2304
	global_load_dwordx4 v[28:31], v[20:21], off offset:2560
	s_nop 0
	global_load_dwordx4 v[20:23], v[20:21], off offset:2816
	v_mad_u64_u32 v[48:49], s[2:3], v133, s14, 0
	s_xor_b64 s[2:3], s[4:5], -1
	s_mov_b64 s[4:5], 0x800
	v_add_u32_e32 v137, 0x11400, v81
	v_lshl_add_u64 v[34:35], v[32:33], 0, s[4:5]
	ds_write2st64_b32 v137, v131, v131 offset1:8
	s_and_saveexec_b64 s[4:5], s[2:3]
	s_cbranch_execz .LBB0_292
	s_waitcnt vmcnt(4)
	v_mov_b32_e32 v24, v131
	v_mov_b32_e32 v25, v131
	v_mov_b32_e32 v26, v131
	v_mov_b32_e32 v27, v131
	s_waitcnt vmcnt(1)
	v_mov_b32_e32 v28, v131
	v_mov_b32_e32 v29, v131
	v_mov_b32_e32 v30, v131
	v_mov_b32_e32 v31, v131
	v_mov_b32_e32 v16, v131
	v_mov_b32_e32 v17, v131
	v_mov_b32_e32 v18, v131
	v_mov_b32_e32 v19, v131
	s_waitcnt vmcnt(0)
	v_mov_b32_e32 v20, v131
	v_mov_b32_e32 v21, v131
	v_mov_b32_e32 v22, v131
	v_mov_b32_e32 v23, v131

; __global__ void __launch_bounds__(NWAVES * 64, 2) fwd_megakernel(Args a) {
;     ...
;             attn_unit(lds, gb * 32 + (l >> 2), 3 + (l & 3), QKVG, a.sinks, a.norm_attn, MIX, SSA);
.LBB0_303:
	v_readlane_b32 s0, v253, 29
	s_nop 2
	s_cmp_lt_u32 s0, 4
	s_cbranch_scc1 .Lprio_skip_q
	s_setprio 1

; __device__ __forceinline__ unsigned xb_ld(unsigned* p)              { return __hip_atomic_load(p, __ATOMIC_RELAXED, __HIP_MEMORY_SCOPE_AGENT); }
; __device__ __forceinline__ void xcd_barrier_complete(unsigned* bar, unsigned x, unsigned& nloc, unsigned& nx) {
;     const unsigned G = gridDim.x * gridDim.y * gridDim.z;
;     unsigned sum, cnt, mine, sp = 0u;
;     for (;;) {
;         sum = 0u; cnt = 0u; mine = 0u;
; #pragma unroll
;         for (unsigned j = 0; j < 16; ++j) { const unsigned c = xb_ld(&bar[XB_XCNT(j)]); sum += c; cnt += (c > 0u) ? 1u : 0u; mine = (j == x) ? c : mine; }
; __device__ __forceinline__ void xcd_barrier(const XcdBarrier& b) {
;     asm volatile("s_waitcnt vmcnt(0)" ::: "memory");
;     __syncthreads();
;     if (threadIdx.x == 0) {
;         unsigned* bar = b.bar;
;         __builtin_amdgcn_s_waitcnt(0);
;         unsigned nloc = b.st[0], nx = b.st[1];
;         if (nloc == 0u) { xcd_barrier_complete(bar, b.x, nloc, nx); b.st[0] = nloc; b.st[1] = nx; }
.LBB0_339:
	s_setprio 0
	s_waitcnt vmcnt(0)
	s_waitcnt vmcnt(0) lgkmcnt(0)
	s_barrier
	s_mov_b64 s[0:1], exec
	v_readlane_b32 s2, v253, 23
	v_readlane_b32 s3, v253, 24
	s_and_b64 s[2:3], s[0:1], s[2:3]
	s_mov_b64 exec, s[2:3]
	s_cbranch_execz .LBB0_391
	s_add_i32 s2, 0, 0x20420
	v_mov_b32_e32 v0, s2
	s_waitcnt vmcnt(0) expcnt(0) lgkmcnt(0)
	ds_read_b32 v2, v0
	s_add_i32 s2, 0, 0x20424
	v_mov_b32_e32 v0, s2
	ds_read_b32 v0, v0
	s_waitcnt lgkmcnt(1)
	v_cmp_ne_u32_e32 vcc, 0, v2
	s_cbranch_vccnz .LBB0_355
	v_readlane_b32 s2, v253, 34
	v_readlane_b32 s3, v253, 35
	s_load_dwordx2 s[6:7], s[2:3], 0x4
	s_add_u32 s2, s96, 0x180200
	s_addc_u32 s3, s97, 0
	s_add_u32 s4, s96, 0x180400
	s_addc_u32 s5, s97, 0
	s_waitcnt lgkmcnt(0)
	s_mul_i32 s33, s6, s99
	s_add_u32 s6, s96, 0x180500
	s_mul_i32 s33, s33, s7
	s_addc_u32 s7, s97, 0
	s_add_u32 s8, s96, 0x180600
	s_addc_u32 s9, s97, 0
	s_add_u32 s10, s96, 0x180700
	s_addc_u32 s11, s97, 0
	s_add_u32 s12, s96, 0x180800
	s_addc_u32 s13, s97, 0
	s_add_u32 s14, s96, 0x180900
	s_addc_u32 s15, s97, 0
	s_add_u32 s16, s96, 0x180a00
	s_addc_u32 s17, s97, 0
	s_add_u32 s18, s96, 0x180b00
	s_addc_u32 s19, s97, 0
	s_add_u32 s20, s96, 0x180c00
	s_addc_u32 s21, s97, 0
	s_add_u32 s22, s96, 0x180d00
	s_addc_u32 s23, s97, 0
	s_add_u32 s24, s96, 0x180e00
	s_addc_u32 s25, s97, 0
	s_add_u32 s26, s96, 0x180f00
	s_addc_u32 s27, s97, 0
	s_add_u32 s28, s96, 0x181000
	s_addc_u32 s29, s97, 0
	s_add_u32 s30, s96, 0x181100
	s_addc_u32 s31, s97, 0
	s_add_u32 s34, s96, 0x181200
	s_addc_u32 s35, s97, 0
	s_add_u32 s36, s96, 0x181300
	s_addc_u32 s37, s97, 0
	s_mov_b32 s44, 1
	v_mov_b32_e32 v16, 0
	s_branch .LBB0_343
